# loop v2: LDS reads spread over MFMA gaps (<=3 per gap) + conflict-free K image swizzle (row&15) in optimistic prompt unit
# speedup vs baseline: 1.0082x; 1.0082x over previous
; #define DMA_K(t, so) do { const char* kb_ = (const char*)(Kg + (size_t)(t) * 64 * LDK); \
;     glds16_pair(kb_, kso0, kso1m, (unsigned)__builtin_amdgcn_readfirstlane((int)(kl0 + (unsigned)((so) + pw)))); } while (0)
; #define DMA_V(t, so) do { const char* vb_ = (const char*)(Vg + (size_t)(t) * 64 * LDK) - 1024; \
;     glds16_pair(vb_, vsoA, vsoB, (unsigned)__builtin_amdgcn_readfirstlane((int)(vl0 + (unsigned)((so) + pw)))); } while (0)
; #define WAITBAR(j) do { if ((j) + 2 < NT) asm volatile("s_waitcnt vmcnt(4)\n\ts_barrier" ::: "memory"); else asm volatile("s_waitcnt vmcnt(0)\n\ts_barrier" ::: "memory"); } while (0)
; #define ROT() do { const int t_ = s0; s0 = s1; s1 = s2; s2 = t_; } while (0)
; #define WB1(j) do { if ((j) + 2 < NT) asm volatile("s_waitcnt vmcnt(6)\n\ts_barrier" ::: "memory"); else asm volatile("s_waitcnt vmcnt(0)\n\ts_barrier" ::: "memory"); } while (0)
; #define WB2(j) do { if ((j) + 2 < NT) asm volatile("s_waitcnt vmcnt(4)\n\ts_barrier" ::: "memory"); else asm volatile("s_waitcnt vmcnt(0)\n\ts_barrier" ::: "memory"); } while (0)
; template <bool SAFE>
; __device__ __forceinline__ bool attn_unit_prompt_t(LAS unsigned char* lds, const bf16* Kg, const bf16* Vg, const bf16* Qrow0, bf16* Orow0, int NT, int qpos0, int h, const float* gnorm) {
;     ...
;   { const int row = 8 * wid + (lane >> 4); kso0 = (unsigned)(row * LDK * 2 + (((lane & 15) ^ (row & 7)) << 4)); kso1 = kso0 + (unsigned)(4 * LDK * 2) + ((kso0 & 64u) ? (unsigned)-64 : 64u);
;     const int kk = wid * 8 + ((lane & 31) >> 2), k = kk, c = (lane >> 5) * 32 + (lane & 3) * 8; vso0 = (unsigned)((k * LDK + c) * 2); }
;   const int pw = wid * 2048; const unsigned kl0 = (unsigned)(uintptr_t)K_lds, vl0 = (unsigned)(uintptr_t)V_lds;
;   const unsigned kso1m = kso1 - 1024u, vsoA = vso0 + 1024u, vsoB = vso0 + 128u;
;     ...
;   DMA_K(0, 0); DMA_V(0, VS(0)); DMA_K(1, SHM_K); DMA_V(1, VS(1));
;   asm volatile("" :: "v"(qr[0]), "v"(qr[1]), "v"(qr[2]), "v"(qr[3]) : "memory");
;     ...
;   const int ph = wid >> 2;
;   if (ph != 0) { asm volatile("s_waitcnt vmcnt(6)\n\ts_barrier" ::: "memory"); }
;   WB1(0); DMA_K(2, s0);
;   QKT(pA0, pA1, K_lds + s1);
;   WB2(0); DMA_V(2, VS(2));
;   BIASMASK(pA0, pA1, 0); rmx = rowmax32(pA0, pA1); PARTIAL(pA0, pA1, alA, true, rmx);
;   ROT();
;     ...
;   WAITBAR(0); DMA_K(2, s0); DMA_V(2, VS(2));
.LBB0_525:
	v_and_b32_e32 v190, 63, v3
	s_lshl_b32 s1, s89, 3
	v_lshrrev_b32_e32 v36, 4, v190
	v_or_b32_e32 v4, s1, v36
	v_mul_lo_u32 v4, v4, s90
	v_bitop3_b32 v5, v36, v3, 15 bitop3:0x78
	v_lshrrev_b32_e32 v6, 3, v3
	v_and_b32_e32 v6, 8, v6
	v_xor_b32_e32 v5, v5, v6
	s_lshl_b32 s31, s89, 11
	s_lshl_b32 s23, s0, 1
	v_lshl_or_b32 v214, v5, 4, v4
	v_and_b32_e32 v4, 4, v3
	s_add_u32 s14, s8, s23
	v_cmp_eq_u32_e32 vcc, 0, v4
	v_lshrrev_b32_e32 v4, 2, v192
	s_addc_u32 s15, s9, 0
	v_or_b32_e32 v4, s1, v4
	s_movk_i32 s1, 0xd00
	s_add_u32 s0, s14, 0xce01200
	v_mul_lo_u32 v4, v4, s1
	s_addc_u32 s1, s15, 0
	s_add_u32 s19, s16, s23
	s_addc_u32 s20, s17, 0
	s_add_u32 s7, s19, 0xce01600
	v_lshlrev_b32_e32 v6, 3, v3
	s_addc_u32 s13, s20, 0
	s_add_i32 s30, s31, 0
	v_and_b32_e32 v5, 32, v3
	v_and_b32_e32 v6, 24, v6
	s_add_u32 s8, s19, 0xce01200
	v_or3_b32 v4, v5, v6, v4
	v_cndmask_b32_e32 v5, v240, v241, vcc
	s_addc_u32 s9, s20, 0
	s_add_i32 s88, 0, 0xc000
	v_lshlrev_b32_e32 v4, 1, v4
	v_add_u32_e32 v215, v214, v5
	s_mov_b32 m0, s30
	s_nop 0
	global_load_lds_dwordx4 v214, s[0:1] offset:0
	global_load_lds_dwordx4 v215, s[0:1] offset:1024
	s_add_i32 s31, s31, s88
	v_add_u32_e32 v216, 0x400, v4
	v_or_b32_e32 v217, 0x80, v4
	s_mov_b32 m0, s31
	s_nop 0
	global_load_lds_dwordx4 v216, s[8:9] offset:0
	global_load_lds_dwordx4 v217, s[8:9] offset:1024
	s_add_u32 s8, s14, 0xce69200
	s_addc_u32 s9, s15, 0
	s_add_i32 s14, s30, 0x4000
	s_mov_b32 m0, s14
	s_nop 0
	global_load_lds_dwordx4 v214, s[8:9] offset:0
	global_load_lds_dwordx4 v215, s[8:9] offset:1024
	s_add_u32 s8, s19, 0xce69200
	s_addc_u32 s9, s20, 0
	s_add_i32 s14, s31, 0x4000
	s_mov_b32 m0, s14
	s_nop 0
	global_load_lds_dwordx4 v216, s[8:9] offset:0
	global_load_lds_dwordx4 v217, s[8:9] offset:1024
	s_waitcnt vmcnt(0)
	s_mov_b64 s[8:9], -1
	s_cmpk_eq_i32 s49, 0x7f
	s_cbranch_scc1 .LBB0_527
	s_waitcnt vmcnt(4)
	s_barrier
	s_mov_b64 s[8:9], 0

; #define LAS __attribute__((address_space(3)))
; __device__ __forceinline__ int v_rd_base(int lane) { return ((lane & 3) << 3) | (((lane >> 2) & 3) << 6) | (((lane >> 4) & 1) << 5) | (((lane >> 5) & 1) << 8); }
; __device__ __forceinline__ float rowmax32(const f32x16& p0, const f32x16& p1) {
;   float pmax = p0[0];
; #pragma unroll
;   for (int r = 1; r < 16; ++r) pmax = fmaxf(pmax, p0[r]);
; #pragma unroll
;   for (int r = 0; r < 16; ++r) pmax = fmaxf(pmax, p1[r]);
;   auto rr = __builtin_amdgcn_permlane32_swap(__float_as_uint(pmax), __float_as_uint(pmax), false, false);
;   return fmaxf(__uint_as_float(rr[0]), __uint_as_float(rr[1]));
; }
; template <bool SAFE>
; __device__ __forceinline__ bool attn_unit_prompt_t(LAS unsigned char* lds, const bf16* Kg, const bf16* Vg, const bf16* Qrow0, bf16* Orow0, int NT, int qpos0, int h, const float* gnorm) {
;     ...
;   const LAS char* vrd = V_lds + v_rd_base(lane);
.LBB0_529:
	s_mulk_i32 s18, 0x600
	s_add_i32 s29, s18, 0
	s_lshl_b32 s26, s11, 7
	v_lshlrev_b32_e32 v4, 3, v191
	s_add_i32 s29, s29, 0x22380
	v_or_b32_e32 v5, s26, v192
	s_add_u32 s8, s0, 0xd0000
	v_or_b32_e32 v4, s6, v4
	v_or_b32_e32 v212, s12, v5
	s_addc_u32 s9, s1, 0
	s_add_i32 s12, s30, 0x8000
	v_lshlrev_b32_e32 v218, 8, v192
	v_lshlrev_b32_e32 v5, 4, v3
	v_lshlrev_b32_e32 v46, 1, v4
	s_movk_i32 s6, 0xf0
	s_mov_b32 m0, s12
	s_nop 0
	global_load_lds_dwordx4 v214, s[8:9] offset:0
	global_load_lds_dwordx4 v215, s[8:9] offset:1024
	s_add_u32 s8, s7, 0xcfc00
	v_add_u32_e32 v37, 0, v218
	v_bitop3_b32 v219, v46, v5, s6 bitop3:0x78
	s_addc_u32 s9, s13, 0
	s_add_i32 s7, s30, 0x14000
	s_mov_b32 m0, s7
	s_nop 0
	global_load_lds_dwordx4 v216, s[8:9] offset:0
	global_load_lds_dwordx4 v217, s[8:9] offset:1024
	v_add_u32_e32 v8, v37, v219
	v_and_b32_e32 v146, 0xf0, v5
	ds_read_b128 v[4:7], v8 offset:8192
	ds_read_b128 v[8:11], v8
	s_waitcnt lgkmcnt(0)
	v_mfma_f32_32x32x16_bf16 v[20:35], v[8:11], v[178:181], 0
	v_bitop3_b32 v220, v46, v146, 32 bitop3:0x36
	v_add_u32_e32 v42, v37, v220
	ds_read_b128 v[38:41], v42 offset:8192
	ds_read_b128 v[42:45], v42
	v_bitop3_b32 v221, v46, v146, 64 bitop3:0x36
	s_movk_i32 s6, 0x60
	v_bitop3_b32 v222, v46, v146, s6 bitop3:0x36
	s_cmpk_lt_u32 s10, 0x1f8
	v_mfma_f32_32x32x16_bf16 v[4:19], v[4:7], v[178:181], 0
	s_waitcnt lgkmcnt(0)
	v_mfma_f32_32x32x16_bf16 v[20:35], v[42:45], v[174:177], v[20:35]
	v_add_u32_e32 v42, v37, v221
	v_add_u32_e32 v37, v37, v222
	v_mfma_f32_32x32x16_bf16 v[4:19], v[38:41], v[174:177], v[4:19]
	ds_read_b128 v[38:41], v42 offset:8192
	ds_read_b128 v[42:45], v42
	s_waitcnt lgkmcnt(0)
	v_mfma_f32_32x32x16_bf16 v[20:35], v[42:45], v[170:173], v[20:35]
	v_mfma_f32_32x32x16_bf16 v[4:19], v[38:41], v[170:173], v[4:19]
	ds_read_b128 v[38:41], v37 offset:8192
	ds_read_b128 v[42:45], v37
	s_waitcnt lgkmcnt(0)
	v_mfma_f32_32x32x16_bf16 v[20:35], v[42:45], v[166:169], v[20:35]
	v_mfma_f32_32x32x16_bf16 v[4:19], v[38:41], v[166:169], v[4:19]
	s_cbranch_scc1 .LBB0_531
	v_lshlrev_b32_e32 v37, 2, v191
	v_sub_u32_e32 v37, v37, v212
	v_lshl_add_u32 v37, v37, 2, s29
	v_add_u32_e32 v38, 0x3fc, v37
	v_add_u32_e32 v40, 0x47c, v37
	ds_read2_b32 v[38:39], v38 offset1:1
	ds_read2_b32 v[40:41], v40 offset1:1
	v_add_u32_e32 v42, 0x404, v37
	v_add_u32_e32 v44, 0x484, v37
	v_add_u32_e32 v46, 0x41c, v37
	v_add_u32_e32 v48, 0x49c, v37
	v_add_u32_e32 v50, 0x424, v37
	v_add_u32_e32 v52, 0x4a4, v37
	v_add_u32_e32 v54, 0x43c, v37
	v_add_u32_e32 v56, 0x4bc, v37
	v_add_u32_e32 v58, 0x444, v37
	v_add_u32_e32 v60, 0x4c4, v37
	v_add_u32_e32 v62, 0x45c, v37
	v_add_u32_e32 v64, 0x4dc, v37
	v_add_u32_e32 v66, 0x464, v37
	v_add_u32_e32 v37, 0x4e4, v37
	ds_read2_b32 v[42:43], v42 offset1:1
	ds_read2_b32 v[44:45], v44 offset1:1
	ds_read2_b32 v[46:47], v46 offset1:1
	ds_read2_b32 v[48:49], v48 offset1:1
	ds_read2_b32 v[50:51], v50 offset1:1
	ds_read2_b32 v[52:53], v52 offset1:1
	ds_read2_b32 v[54:55], v54 offset1:1
	ds_read2_b32 v[56:57], v56 offset1:1
	ds_read2_b32 v[58:59], v58 offset1:1
	ds_read2_b32 v[60:61], v60 offset1:1
	ds_read2_b32 v[62:63], v62 offset1:1
	ds_read2_b32 v[64:65], v64 offset1:1
	ds_read2_b32 v[66:67], v66 offset1:1
	s_waitcnt lgkmcnt(14)
	v_pk_add_f32 v[20:21], v[20:21], v[38:39]
	ds_read2_b32 v[38:39], v37 offset1:1
	s_waitcnt lgkmcnt(3)
	v_pk_add_f32 v[32:33], v[32:33], v[62:63]
	v_pk_add_f32 v[30:31], v[30:31], v[58:59]
	s_waitcnt lgkmcnt(1)
	v_pk_add_f32 v[34:35], v[34:35], v[66:67]
	v_pk_add_f32 v[28:29], v[28:29], v[54:55]
	v_pk_add_f32 v[26:27], v[26:27], v[50:51]
	v_pk_add_f32 v[24:25], v[24:25], v[46:47]
	v_pk_add_f32 v[22:23], v[22:23], v[42:43]
	s_waitcnt lgkmcnt(0)
	v_pk_add_f32 v[18:19], v[18:19], v[38:39]
	v_pk_add_f32 v[16:17], v[16:17], v[64:65]
	v_pk_add_f32 v[14:15], v[14:15], v[60:61]
	v_pk_add_f32 v[12:13], v[12:13], v[56:57]
	v_pk_add_f32 v[10:11], v[10:11], v[52:53]
	v_pk_add_f32 v[8:9], v[8:9], v[48:49]
	v_pk_add_f32 v[6:7], v[6:7], v[44:45]
	v_pk_add_f32 v[4:5], v[4:5], v[40:41]
.LBB0_531:
	v_lshlrev_b32_e32 v37, 3, v190
	v_lshlrev_b32_e32 v39, 4, v190
	v_and_b32_e32 v38, 24, v37
	v_and_b32_e32 v39, 0xc0, v39
	v_lshlrev_b32_e32 v40, 1, v190
	v_and_b32_e32 v40, 32, v40
	v_and_b32_e32 v37, 0x100, v37
	v_add3_u32 v38, 0, v38, v39
	s_and_b32 s6, s22, 0x3fffffc0
	v_add3_u32 v194, v38, v40, v37
	v_and_b32_e32 v36, 1, v36
	v_and_b32_e32 v37, 1, v3
	s_lshl_b32 s6, s6, 2
	v_cmp_eq_u32_e32 vcc, v36, v37
	s_add_i32 s27, s6, 0
	s_mov_b32 s6, 0x5040100
	v_cndmask_b32_e32 v36, 0, v242, vcc
	v_perm_b32 v162, v36, v36, s6
	v_max_f32_e32 v36, v21, v21
	v_max_f32_e32 v38, v20, v20
	v_max_f32_e32 v36, v38, v36
	v_max3_f32 v36, v36, v22, v23
	v_max3_f32 v36, v36, v24, v25
	v_max3_f32 v36, v36, v26, v27
	v_max3_f32 v36, v36, v28, v29
	v_max3_f32 v36, v36, v30, v31
	v_max3_f32 v36, v36, v32, v33
	v_max3_f32 v36, v36, v34, v35
	v_max3_f32 v36, v36, v4, v5
	v_max3_f32 v36, v36, v6, v7
	v_max3_f32 v36, v36, v8, v9
	v_max3_f32 v36, v36, v10, v11
	v_max3_f32 v36, v36, v12, v13
	v_max3_f32 v36, v36, v14, v15
	v_max3_f32 v36, v36, v16, v17
	v_max3_f32 v36, v36, v18, v19
	v_mov_b32_e32 v38, v36
	s_nop 1
	v_permlane32_swap_b32_e32 v36, v38
	v_max_f32_e32 v38, v38, v38
	v_max_f32_e32 v36, v36, v36
	v_max_f32_e32 v36, v36, v38
	v_add_f32_e32 v213, 0, v36
	v_sub_f32_e32 v20, v20, v213
	v_sub_f32_e32 v21, v21, v213
	v_sub_f32_e32 v22, v22, v213
	v_sub_f32_e32 v23, v23, v213
	v_sub_f32_e32 v24, v24, v213
	v_sub_f32_e32 v25, v25, v213
	v_sub_f32_e32 v26, v26, v213
	v_sub_f32_e32 v27, v27, v213
	v_sub_f32_e32 v28, v28, v213
	v_sub_f32_e32 v29, v29, v213
	v_sub_f32_e32 v30, v30, v213
	v_sub_f32_e32 v31, v31, v213
; #define LAS __attribute__((address_space(3)))
; __device__ __forceinline__ int v_rd_base(int lane) { return ((lane & 3) << 3) | (((lane >> 2) & 3) << 6) | (((lane >> 4) & 1) << 5) | (((lane >> 5) & 1) << 8); }
; template <bool SAFE>
; __device__ __forceinline__ bool attn_unit_prompt_t(LAS unsigned char* lds, const bf16* Kg, const bf16* Vg, const bf16* Qrow0, bf16* Orow0, int NT, int qpos0, int h, const float* gnorm) {
;     ...
;   const LAS char* vrd = V_lds + v_rd_base(lane);
;     ...
;   const short one_ = (((lane >> 4) & 1) == (lane & 1)) ? (short)16256 : (short)0;
;   const bf16x8 ones = {one_, one_, one_, one_, one_, one_, one_, one_};
;   f32x16 pA0, pA1, pB0, pB1; float alA = 1.f, alB = 1.f, rmx;
;   int s0 = 2 * SHM_K, s1 = 0, s2 = SHM_K;
	v_sub_f32_e32 v32, v32, v213
	v_sub_f32_e32 v33, v33, v213
	v_sub_f32_e32 v34, v34, v213
	v_sub_f32_e32 v35, v35, v213
	v_exp_f32_e32 v186, v20
	v_exp_f32_e32 v187, v21
	v_exp_f32_e32 v188, v22
	v_exp_f32_e32 v189, v23
	v_exp_f32_e32 v246, v24
	v_exp_f32_e32 v247, v25
	v_exp_f32_e32 v248, v26
	v_exp_f32_e32 v249, v27
	v_exp_f32_e32 v150, v28
	v_exp_f32_e32 v151, v29
	v_exp_f32_e32 v152, v30
	v_exp_f32_e32 v153, v31
	v_exp_f32_e32 v154, v32
	v_exp_f32_e32 v156, v33
	v_exp_f32_e32 v155, v34
	v_exp_f32_e32 v157, v35
	s_lshl_b32 s19, s11, 1
	s_add_i32 s27, s27, 0x1c000
	v_sub_f32_e32 v82, 0, v213
	v_sub_f32_e32 v98, v4, v213
	v_max_f32_e32 v4, v36, v36
	v_and_b32_e32 v193, 48, v3
	s_mov_b32 s35, 1
	v_mov_b32_e32 v163, v162
	v_mov_b32_e32 v164, v162
	v_mov_b32_e32 v165, v162
	v_mov_b32_e32 v83, v82
	v_mov_b32_e32 v84, v82
	v_mov_b32_e32 v85, v82
	v_mov_b32_e32 v86, v82
	v_mov_b32_e32 v87, v82
	v_mov_b32_e32 v88, v82
	v_mov_b32_e32 v89, v82
	v_mov_b32_e32 v90, v82
	v_mov_b32_e32 v91, v82
	v_mov_b32_e32 v92, v82
	v_mov_b32_e32 v93, v82
	v_mov_b32_e32 v94, v82
	v_mov_b32_e32 v95, v82
	v_mov_b32_e32 v96, v82
	v_mov_b32_e32 v97, v82
	v_sub_f32_e32 v113, v19, v213
	v_sub_f32_e32 v112, v18, v213
	v_sub_f32_e32 v111, v17, v213
	v_sub_f32_e32 v110, v16, v213
	v_sub_f32_e32 v109, v15, v213
	v_sub_f32_e32 v108, v14, v213
	v_sub_f32_e32 v107, v13, v213
	v_sub_f32_e32 v106, v12, v213
	v_sub_f32_e32 v105, v11, v213
	v_sub_f32_e32 v104, v10, v213
	v_sub_f32_e32 v103, v9, v213
	v_sub_f32_e32 v102, v8, v213
	v_sub_f32_e32 v101, v7, v213
	v_sub_f32_e32 v100, v6, v213
	v_sub_f32_e32 v99, v5, v213
	s_cmpk_gt_u32 s10, 0x1f3
	v_cmp_gt_u32_e64 s[6:7], 32, v190
	v_lshlrev_b32_e32 v195, 6, v37
	v_lshl_or_b32 v8, s24, 7, v196
	v_max_f32_e32 v210, 0, v4
	v_add_u32_e32 v223, s27, v193
	s_cbranch_scc1 .LBB0_547
	s_add_i32 s20, s19, -3
	v_or_b32_e32 v4, 32, v8
	v_xad_u32 v10, v4, v146, v218
	v_or_b32_e32 v4, 64, v8
	s_cmp_lg_u32 s28, 0
	v_mov_b32_e32 v66, v197
	v_mov_b32_e32 v67, v197
	v_xad_u32 v11, v4, v146, v218
	v_or_b32_e32 v4, 0x60, v8
	s_cselect_b64 s[10:11], -1, 0
	s_add_u32 s21, s16, s92
	v_mov_b32_e32 v68, v197
	v_mov_b32_e32 v69, v197
	v_mov_b32_e32 v70, v197
	v_mov_b32_e32 v71, v197
	v_mov_b32_e32 v72, v197
	v_mov_b32_e32 v73, v197
	v_mov_b32_e32 v74, v197
	v_mov_b32_e32 v75, v197
	v_mov_b32_e32 v76, v197
	v_mov_b32_e32 v77, v197
	v_mov_b32_e32 v78, v197
	v_mov_b32_e32 v79, v197
	v_mov_b32_e32 v80, v197
	v_mov_b32_e32 v81, v197
	v_mov_b64_e32 v[50:51], v[66:67]
	v_mov_b64_e32 v[34:35], v[66:67]
	v_mov_b64_e32 v[18:19], v[66:67]
	v_xad_u32 v9, v8, v146, v218
	v_xad_u32 v12, v4, v146, v218
	s_mov_b32 s8, 0
	v_lshl_add_u32 v13, v192, 2, s27
	s_addc_u32 s34, s17, 0
	v_mov_b32_e32 v182, v197
	v_mov_b32_e32 v183, v197
	v_mov_b32_e32 v184, v197
	v_mov_b32_e32 v185, v197
	s_mov_b32 s65, 0x8000
	s_movk_i32 s64, 0x4000
	s_mov_b32 s36, 0x10000
	s_mov_b64 s[12:13], 0
	v_mov_b64_e32 v[52:53], v[68:69]
	v_mov_b64_e32 v[54:55], v[70:71]
	v_mov_b64_e32 v[56:57], v[72:73]
	v_mov_b64_e32 v[58:59], v[74:75]
	v_mov_b64_e32 v[60:61], v[76:77]
	v_mov_b64_e32 v[62:63], v[78:79]
	v_mov_b64_e32 v[64:65], v[80:81]
	v_mov_b64_e32 v[36:37], v[68:69]
	v_mov_b64_e32 v[38:39], v[70:71]
	v_mov_b64_e32 v[40:41], v[72:73]
	v_mov_b64_e32 v[42:43], v[74:75]
	v_mov_b64_e32 v[44:45], v[76:77]
	v_mov_b64_e32 v[46:47], v[78:79]
	v_mov_b64_e32 v[48:49], v[80:81]
	v_mov_b64_e32 v[20:21], v[68:69]
	v_mov_b64_e32 v[22:23], v[70:71]
	v_mov_b64_e32 v[24:25], v[72:73]
	v_mov_b64_e32 v[26:27], v[74:75]
	v_mov_b64_e32 v[28:29], v[76:77]
	v_mov_b64_e32 v[30:31], v[78:79]
	v_mov_b64_e32 v[32:33], v[80:81]
	v_cvt_pk_bf16_f32 v130, v186, v187
	v_cvt_pk_bf16_f32 v131, v188, v189
	v_cvt_pk_bf16_f32 v132, v246, v247
	v_cvt_pk_bf16_f32 v133, v248, v249
	v_cvt_pk_bf16_f32 v134, v150, v151
	v_cvt_pk_bf16_f32 v135, v152, v153
	v_cvt_pk_bf16_f32 v136, v154, v156
	v_cvt_pk_bf16_f32 v137, v155, v157
	s_and_b32 s66, s36, 0xc000
	v_add_u32_e32 v147, s66, v194
	ds_read_b64_tr_b16 v[246:247], v147 offset:49152
	ds_read_b64_tr_b16 v[248:249], v147 offset:51200
	ds_read_b64_tr_b16 v[250:251], v147 offset:49664
	ds_read_b64_tr_b16 v[252:253], v147 offset:51712
	ds_read_b64_tr_b16 v[198:199], v147 offset:50176
	ds_read_b64_tr_b16 v[200:201], v147 offset:52224
	ds_read_b64_tr_b16 v[202:203], v147 offset:50688
	ds_read_b64_tr_b16 v[204:205], v147 offset:52736
	ds_read_b64_tr_b16 v[206:207], v147 offset:53248
	ds_read_b64_tr_b16 v[208:209], v147 offset:55296
	ds_read_b64_tr_b16 v[236:237], v147 offset:53760
	ds_read_b64_tr_b16 v[238:239], v147 offset:55808
	ds_read_b64_tr_b16 v[240:241], v147 offset:54272
	ds_read_b64_tr_b16 v[242:243], v147 offset:56320
	ds_read_b64_tr_b16 v[232:233], v147 offset:54784
	ds_read_b64_tr_b16 v[234:235], v147 offset:56832
; #define LAS __attribute__((address_space(3)))
; __device__ __forceinline__ int v_rd_base(int lane) { return ((lane & 3) << 3) | (((lane >> 2) & 3) << 6) | (((lane >> 4) & 1) << 5) | (((lane >> 5) & 1) << 8); }
; template <bool SAFE>
; __device__ __forceinline__ bool attn_unit_prompt_t(LAS unsigned char* lds, const bf16* Kg, const bf16* Vg, const bf16* Qrow0, bf16* Orow0, int NT, int qpos0, int h, const float* gnorm) {
;     ...
;   const LAS char* vrd = V_lds + v_rd_base(lane);
.Lmy533:
	s_mov_b32 s37, s64
	s_add_i32 s32, s37, 0
	s_waitcnt vmcnt(4)
	s_barrier
	v_add_u32_e32 v161, s32, v9
	v_add_u32_e32 v211, s32, v10
	ds_read_b128 v[4:7], v161
	ds_read_b128 v[14:17], v161 offset:8192
	s_mov_b32 s64, s8
	s_and_b32 s66, s36, 0xc000
	v_add_u32_e32 v147, s66, v194
	s_add_i32 s67, s36, 0x4000
	s_and_b32 s67, s67, 0xc000
	v_add_u32_e32 v160, s67, v194
	s_waitcnt lgkmcnt(14)
	v_mfma_f32_32x32x16_bf16 v[66:81], v[130:133], v[246:249], v[66:81]
	v_exp_f32_e32 v98, v98
	ds_read_b64_tr_b16 v[246:247], v147 offset:57344
	ds_read_b64_tr_b16 v[248:249], v147 offset:59392
	ds_read_b128 v[148:151], v211
	s_waitcnt lgkmcnt(14)
	v_mfma_f32_32x32x16_bf16 v[50:65], v[130:133], v[250:253], v[50:65]
	v_exp_f32_e32 v99, v99
	ds_read_b64_tr_b16 v[250:251], v147 offset:57856
	ds_read_b64_tr_b16 v[252:253], v147 offset:59904
	ds_read_b128 v[152:155], v211 offset:8192
	s_waitcnt lgkmcnt(14)
	v_mfma_f32_32x32x16_bf16 v[34:49], v[130:133], v[198:201], v[34:49]
	v_exp_f32_e32 v100, v100
	ds_read_b64_tr_b16 v[198:199], v147 offset:58368
	ds_read_b64_tr_b16 v[200:201], v147 offset:60416
	v_add_u32_e32 v161, s32, v11
	v_add_u32_e32 v211, s32, v12
	s_waitcnt lgkmcnt(14)
	v_mfma_f32_32x32x16_bf16 v[18:33], v[130:133], v[202:205], v[18:33]
	v_exp_f32_e32 v101, v101
	v_exp_f32_e32 v102, v102
	ds_read_b64_tr_b16 v[202:203], v147 offset:58880
	ds_read_b64_tr_b16 v[204:205], v147 offset:60928
	v_mfma_f32_16x16x32_bf16 v[182:185], v[130:133], v[162:165], v[182:185]
	ds_read_b128 v[156:159], v161
	ds_read_b128 v[186:189], v161 offset:8192
	s_waitcnt lgkmcnt(14)
	v_mfma_f32_32x32x16_bf16 v[66:81], v[134:137], v[206:209], v[66:81]
	v_exp_f32_e32 v103, v103
	ds_read_b64_tr_b16 v[206:207], v147 offset:61440
	ds_read_b64_tr_b16 v[208:209], v147 offset:63488
	ds_read_b128 v[224:227], v211
	s_waitcnt lgkmcnt(14)
	v_mfma_f32_32x32x16_bf16 v[50:65], v[134:137], v[236:239], v[50:65]
	v_exp_f32_e32 v104, v104
	ds_read_b64_tr_b16 v[236:237], v147 offset:61952
	ds_read_b64_tr_b16 v[238:239], v147 offset:64000
	ds_read_b128 v[228:231], v211 offset:8192
	s_waitcnt lgkmcnt(14)
	v_mfma_f32_32x32x16_bf16 v[34:49], v[134:137], v[240:243], v[34:49]
	v_exp_f32_e32 v105, v105
	v_exp_f32_e32 v106, v106
	ds_read_b64_tr_b16 v[240:241], v147 offset:62464
	ds_read_b64_tr_b16 v[242:243], v147 offset:64512
	s_waitcnt lgkmcnt(14)
	v_mfma_f32_32x32x16_bf16 v[18:33], v[134:137], v[232:235], v[18:33]
	v_exp_f32_e32 v107, v107
	v_exp_f32_e32 v108, v108
	ds_read_b64_tr_b16 v[232:233], v147 offset:62976
	ds_read_b64_tr_b16 v[234:235], v147 offset:65024
	v_mfma_f32_16x16x32_bf16 v[182:185], v[134:137], v[162:165], v[182:185]
	s_add_u32 s48, s0, s12
	s_addc_u32 s54, s1, s13
	s_add_u32 s8, s48, 0x138000
	s_addc_u32 s9, s54, 0
	s_add_i32 s15, s64, s30
	s_add_u32 s55, s21, s12
	s_addc_u32 s93, s34, s13
	s_mov_b32 m0, s15
	s_nop 0
	global_load_lds_dwordx4 v214, s[8:9] offset:0
	global_load_lds_dwordx4 v215, s[8:9] offset:1024
	s_waitcnt lgkmcnt(14)
	v_mfma_f32_32x32x16_bf16 v[130:145], v[4:7], v[178:181], v[82:97]
	s_add_u32 s8, s55, 0xcf39200
	s_addc_u32 s9, s93, 0
	s_add_i32 s15, s36, 0xffffc000
	s_and_b32 s15, s15, 0xc000
	s_add_i32 s15, s15, s31
	s_mov_b32 m0, s15
	s_nop 0
	global_load_lds_dwordx4 v216, s[8:9] offset:0
	global_load_lds_dwordx4 v217, s[8:9] offset:1024
	s_waitcnt lgkmcnt(14)
	v_mfma_f32_32x32x16_bf16 v[130:145], v[148:151], v[174:177], v[130:145]
	v_exp_f32_e32 v109, v109
	v_exp_f32_e32 v110, v110
	s_waitcnt lgkmcnt(11)
	v_mfma_f32_32x32x16_bf16 v[130:145], v[156:159], v[170:173], v[130:145]
	v_exp_f32_e32 v111, v111
	v_exp_f32_e32 v112, v112
	s_waitcnt lgkmcnt(7)
	v_mfma_f32_32x32x16_bf16 v[130:145], v[224:227], v[166:169], v[130:145]
	v_exp_f32_e32 v113, v113
	s_waitcnt lgkmcnt(14)
	v_mfma_f32_32x32x16_bf16 v[114:129], v[14:17], v[178:181], v[82:97]
	v_cvt_pk_bf16_f32 v98, v98, v99
	v_cvt_pk_bf16_f32 v99, v100, v101
	s_waitcnt lgkmcnt(14)
	v_mfma_f32_32x32x16_bf16 v[114:129], v[152:155], v[174:177], v[114:129]
	v_cvt_pk_bf16_f32 v100, v102, v103
	v_cvt_pk_bf16_f32 v101, v104, v105
	s_waitcnt lgkmcnt(10)
	v_mfma_f32_32x32x16_bf16 v[114:129], v[186:189], v[170:173], v[114:129]
	v_cvt_pk_bf16_f32 v102, v106, v107
	v_cvt_pk_bf16_f32 v103, v108, v109
	s_waitcnt lgkmcnt(4)
	v_mfma_f32_32x32x16_bf16 v[114:129], v[228:231], v[166:169], v[114:129]
	v_cvt_pk_bf16_f32 v104, v110, v111
	v_cvt_pk_bf16_f32 v105, v112, v113
	s_waitcnt lgkmcnt(14)
	v_mfma_f32_32x32x16_bf16 v[66:81], v[98:101], v[246:249], v[66:81]
	v_exp_f32_e32 v130, v130
	v_exp_f32_e32 v131, v131
	ds_read_b64_tr_b16 v[246:247], v160 offset:49152
	ds_read_b64_tr_b16 v[248:249], v160 offset:51200
	s_waitcnt lgkmcnt(14)
	v_mfma_f32_32x32x16_bf16 v[50:65], v[98:101], v[250:253], v[50:65]
	v_exp_f32_e32 v132, v132
	v_exp_f32_e32 v133, v133
	ds_read_b64_tr_b16 v[250:251], v160 offset:49664
	ds_read_b64_tr_b16 v[252:253], v160 offset:51712
	s_waitcnt lgkmcnt(14)
	v_mfma_f32_32x32x16_bf16 v[34:49], v[98:101], v[198:201], v[34:49]
	v_exp_f32_e32 v134, v134
	v_exp_f32_e32 v135, v135
	ds_read_b64_tr_b16 v[198:199], v160 offset:50176
	ds_read_b64_tr_b16 v[200:201], v160 offset:52224
	s_waitcnt lgkmcnt(14)
	v_mfma_f32_32x32x16_bf16 v[18:33], v[98:101], v[202:205], v[18:33]
	v_exp_f32_e32 v136, v136
	v_exp_f32_e32 v137, v137
	ds_read_b64_tr_b16 v[202:203], v160 offset:50688
	ds_read_b64_tr_b16 v[204:205], v160 offset:52736
	v_mfma_f32_16x16x32_bf16 v[182:185], v[98:101], v[162:165], v[182:185]
	v_exp_f32_e32 v138, v138
	v_exp_f32_e32 v139, v139
	s_waitcnt lgkmcnt(14)
	v_mfma_f32_32x32x16_bf16 v[66:81], v[102:105], v[206:209], v[66:81]
	v_exp_f32_e32 v140, v140
	v_exp_f32_e32 v141, v141
	ds_read_b64_tr_b16 v[206:207], v160 offset:53248
	ds_read_b64_tr_b16 v[208:209], v160 offset:55296
	s_waitcnt lgkmcnt(14)
	v_mfma_f32_32x32x16_bf16 v[50:65], v[102:105], v[236:239], v[50:65]
	v_exp_f32_e32 v142, v142
	v_exp_f32_e32 v143, v143
	ds_read_b64_tr_b16 v[236:237], v160 offset:53760
	ds_read_b64_tr_b16 v[238:239], v160 offset:55808
	s_waitcnt lgkmcnt(14)
	v_mfma_f32_32x32x16_bf16 v[34:49], v[102:105], v[240:243], v[34:49]
	v_exp_f32_e32 v144, v144
	v_exp_f32_e32 v145, v145
	ds_read_b64_tr_b16 v[240:241], v160 offset:54272
	ds_read_b64_tr_b16 v[242:243], v160 offset:56320
	s_waitcnt lgkmcnt(14)
	v_mfma_f32_32x32x16_bf16 v[18:33], v[102:105], v[232:235], v[18:33]
	v_cvt_pk_bf16_f32 v130, v130, v131
	v_cvt_pk_bf16_f32 v131, v132, v133
	v_cvt_pk_bf16_f32 v132, v134, v135
	v_cvt_pk_bf16_f32 v133, v136, v137
	ds_read_b64_tr_b16 v[232:233], v160 offset:54784
	ds_read_b64_tr_b16 v[234:235], v160 offset:56832
	v_mfma_f32_16x16x32_bf16 v[182:185], v[102:105], v[162:165], v[182:185]
	v_cvt_pk_bf16_f32 v134, v138, v139
	v_cvt_pk_bf16_f32 v135, v140, v141
	v_cvt_pk_bf16_f32 v136, v142, v143
	v_cvt_pk_bf16_f32 v137, v144, v145
	s_add_i32 s32, s65, 0
	s_waitcnt vmcnt(4)
	s_barrier
; #define LAS __attribute__((address_space(3)))
; __device__ __forceinline__ int v_rd_base(int lane) { return ((lane & 3) << 3) | (((lane >> 2) & 3) << 6) | (((lane >> 4) & 1) << 5) | (((lane >> 5) & 1) << 8); }
; template <bool SAFE>
; __device__ __forceinline__ bool attn_unit_prompt_t(LAS unsigned char* lds, const bf16* Kg, const bf16* Vg, const bf16* Qrow0, bf16* Orow0, int NT, int qpos0, int h, const float* gnorm) {
;     ...
;   const LAS char* vrd = V_lds + v_rd_base(lane);
	v_add_u32_e32 v161, s32, v9
	v_add_u32_e32 v211, s32, v10
	ds_read_b128 v[4:7], v161
	ds_read_b128 v[14:17], v161 offset:8192
	s_add_i32 s67, s36, 0x8000
	s_and_b32 s67, s67, 0xc000
	v_add_u32_e32 v147, s67, v194
	s_waitcnt lgkmcnt(14)
	v_mfma_f32_32x32x16_bf16 v[66:81], v[130:133], v[246:249], v[66:81]
	v_exp_f32_e32 v114, v114
	ds_read_b64_tr_b16 v[246:247], v160 offset:57344
	ds_read_b64_tr_b16 v[248:249], v160 offset:59392
	ds_read_b128 v[148:151], v211
	s_waitcnt lgkmcnt(14)
	v_mfma_f32_32x32x16_bf16 v[50:65], v[130:133], v[250:253], v[50:65]
	v_exp_f32_e32 v115, v115
	ds_read_b64_tr_b16 v[250:251], v160 offset:57856
	ds_read_b64_tr_b16 v[252:253], v160 offset:59904
	ds_read_b128 v[152:155], v211 offset:8192
	s_waitcnt lgkmcnt(14)
	v_mfma_f32_32x32x16_bf16 v[34:49], v[130:133], v[198:201], v[34:49]
	v_exp_f32_e32 v116, v116
	ds_read_b64_tr_b16 v[198:199], v160 offset:58368
	ds_read_b64_tr_b16 v[200:201], v160 offset:60416
	v_add_u32_e32 v161, s32, v11
	v_add_u32_e32 v211, s32, v12
	s_waitcnt lgkmcnt(14)
	v_mfma_f32_32x32x16_bf16 v[18:33], v[130:133], v[202:205], v[18:33]
	v_exp_f32_e32 v117, v117
	v_exp_f32_e32 v118, v118
	ds_read_b64_tr_b16 v[202:203], v160 offset:58880
	ds_read_b64_tr_b16 v[204:205], v160 offset:60928
	v_mfma_f32_16x16x32_bf16 v[182:185], v[130:133], v[162:165], v[182:185]
	ds_read_b128 v[156:159], v161
	ds_read_b128 v[186:189], v161 offset:8192
	s_waitcnt lgkmcnt(14)
	v_mfma_f32_32x32x16_bf16 v[66:81], v[134:137], v[206:209], v[66:81]
	v_exp_f32_e32 v119, v119
	ds_read_b64_tr_b16 v[206:207], v160 offset:61440
	ds_read_b64_tr_b16 v[208:209], v160 offset:63488
	ds_read_b128 v[224:227], v211
	s_waitcnt lgkmcnt(14)
	v_mfma_f32_32x32x16_bf16 v[50:65], v[134:137], v[236:239], v[50:65]
	v_exp_f32_e32 v120, v120
	ds_read_b64_tr_b16 v[236:237], v160 offset:61952
	ds_read_b64_tr_b16 v[238:239], v160 offset:64000
	ds_read_b128 v[228:231], v211 offset:8192
	s_waitcnt lgkmcnt(14)
	v_mfma_f32_32x32x16_bf16 v[34:49], v[134:137], v[240:243], v[34:49]
	v_exp_f32_e32 v121, v121
	v_exp_f32_e32 v122, v122
	ds_read_b64_tr_b16 v[240:241], v160 offset:62464
	ds_read_b64_tr_b16 v[242:243], v160 offset:64512
	s_waitcnt lgkmcnt(14)
	v_mfma_f32_32x32x16_bf16 v[18:33], v[134:137], v[232:235], v[18:33]
	v_exp_f32_e32 v123, v123
	v_exp_f32_e32 v124, v124
	ds_read_b64_tr_b16 v[232:233], v160 offset:62976
	ds_read_b64_tr_b16 v[234:235], v160 offset:65024
	v_mfma_f32_16x16x32_bf16 v[182:185], v[134:137], v[162:165], v[182:185]
	s_add_u32 s14, s48, 0x1a0000
	s_addc_u32 s15, s54, 0
	s_add_i32 s48, s37, s30
	s_mov_b32 m0, s48
	s_nop 0
	global_load_lds_dwordx4 v214, s[14:15] offset:0
	global_load_lds_dwordx4 v215, s[14:15] offset:1024
	s_waitcnt lgkmcnt(14)
	v_mfma_f32_32x32x16_bf16 v[130:145], v[4:7], v[178:181], v[82:97]
	s_add_u32 s14, s55, 0xcfa1200
	s_addc_u32 s15, s93, 0
	s_add_i32 s48, s66, s31
	s_mov_b32 m0, s48
	s_nop 0
	global_load_lds_dwordx4 v216, s[14:15] offset:0
	global_load_lds_dwordx4 v217, s[14:15] offset:1024
	s_waitcnt lgkmcnt(14)
	v_mfma_f32_32x32x16_bf16 v[130:145], v[148:151], v[174:177], v[130:145]
	v_exp_f32_e32 v125, v125
	v_exp_f32_e32 v126, v126
	s_waitcnt lgkmcnt(11)
	v_mfma_f32_32x32x16_bf16 v[130:145], v[156:159], v[170:173], v[130:145]
	v_exp_f32_e32 v127, v127
	v_exp_f32_e32 v128, v128
	s_waitcnt lgkmcnt(7)
	v_mfma_f32_32x32x16_bf16 v[130:145], v[224:227], v[166:169], v[130:145]
	v_exp_f32_e32 v129, v129
	s_waitcnt lgkmcnt(14)
	v_mfma_f32_32x32x16_bf16 v[98:113], v[14:17], v[178:181], v[82:97]
	v_cvt_pk_bf16_f32 v114, v114, v115
	v_cvt_pk_bf16_f32 v115, v116, v117
	s_waitcnt lgkmcnt(14)
	v_mfma_f32_32x32x16_bf16 v[98:113], v[152:155], v[174:177], v[98:113]
	v_cvt_pk_bf16_f32 v116, v118, v119
	v_cvt_pk_bf16_f32 v117, v120, v121
	s_waitcnt lgkmcnt(10)
	v_mfma_f32_32x32x16_bf16 v[98:113], v[186:189], v[170:173], v[98:113]
	v_cvt_pk_bf16_f32 v118, v122, v123
	v_cvt_pk_bf16_f32 v119, v124, v125
	s_waitcnt lgkmcnt(4)
	v_mfma_f32_32x32x16_bf16 v[98:113], v[228:231], v[166:169], v[98:113]
	v_cvt_pk_bf16_f32 v120, v126, v127
	v_cvt_pk_bf16_f32 v121, v128, v129
	s_waitcnt lgkmcnt(14)
	v_mfma_f32_32x32x16_bf16 v[66:81], v[114:117], v[246:249], v[66:81]
	v_exp_f32_e32 v130, v130
	v_exp_f32_e32 v131, v131
	ds_read_b64_tr_b16 v[246:247], v147 offset:49152
	ds_read_b64_tr_b16 v[248:249], v147 offset:51200
	s_waitcnt lgkmcnt(14)
	v_mfma_f32_32x32x16_bf16 v[50:65], v[114:117], v[250:253], v[50:65]
	v_exp_f32_e32 v132, v132
	v_exp_f32_e32 v133, v133
	ds_read_b64_tr_b16 v[250:251], v147 offset:49664
	ds_read_b64_tr_b16 v[252:253], v147 offset:51712
	s_waitcnt lgkmcnt(14)
	v_mfma_f32_32x32x16_bf16 v[34:49], v[114:117], v[198:201], v[34:49]
	v_exp_f32_e32 v134, v134
	v_exp_f32_e32 v135, v135
	ds_read_b64_tr_b16 v[198:199], v147 offset:50176
	ds_read_b64_tr_b16 v[200:201], v147 offset:52224
	s_waitcnt lgkmcnt(14)
	v_mfma_f32_32x32x16_bf16 v[18:33], v[114:117], v[202:205], v[18:33]
	v_exp_f32_e32 v136, v136
	v_exp_f32_e32 v137, v137
	ds_read_b64_tr_b16 v[202:203], v147 offset:50688
	ds_read_b64_tr_b16 v[204:205], v147 offset:52736
	v_mfma_f32_16x16x32_bf16 v[182:185], v[114:117], v[162:165], v[182:185]
	v_exp_f32_e32 v138, v138
	v_exp_f32_e32 v139, v139
	s_waitcnt lgkmcnt(14)
	v_mfma_f32_32x32x16_bf16 v[66:81], v[118:121], v[206:209], v[66:81]
	v_exp_f32_e32 v140, v140
	v_exp_f32_e32 v141, v141
	ds_read_b64_tr_b16 v[206:207], v147 offset:53248
	ds_read_b64_tr_b16 v[208:209], v147 offset:55296
	s_waitcnt lgkmcnt(14)
	v_mfma_f32_32x32x16_bf16 v[50:65], v[118:121], v[236:239], v[50:65]
	v_exp_f32_e32 v142, v142
	v_exp_f32_e32 v143, v143
	ds_read_b64_tr_b16 v[236:237], v147 offset:53760
	ds_read_b64_tr_b16 v[238:239], v147 offset:55808
	s_waitcnt lgkmcnt(14)
	v_mfma_f32_32x32x16_bf16 v[34:49], v[118:121], v[240:243], v[34:49]
	v_exp_f32_e32 v144, v144
	v_exp_f32_e32 v145, v145
	ds_read_b64_tr_b16 v[240:241], v147 offset:54272
	ds_read_b64_tr_b16 v[242:243], v147 offset:56320
	s_waitcnt lgkmcnt(14)
	v_mfma_f32_32x32x16_bf16 v[18:33], v[118:121], v[232:235], v[18:33]
	v_cvt_pk_bf16_f32 v130, v130, v131
	v_cvt_pk_bf16_f32 v131, v132, v133
	v_cvt_pk_bf16_f32 v132, v134, v135
	v_cvt_pk_bf16_f32 v133, v136, v137
	ds_read_b64_tr_b16 v[232:233], v147 offset:54784
	ds_read_b64_tr_b16 v[234:235], v147 offset:56832
	v_mfma_f32_16x16x32_bf16 v[182:185], v[118:121], v[162:165], v[182:185]
	v_cvt_pk_bf16_f32 v134, v138, v139
	v_cvt_pk_bf16_f32 v135, v140, v141
	v_cvt_pk_bf16_f32 v136, v142, v143
	v_cvt_pk_bf16_f32 v137, v144, v145
	s_add_i32 s35, s35, 2
	s_add_i32 s36, s36, 0x8000
	s_add_u32 s12, s12, 0xd0000
	s_addc_u32 s13, s13, 0
	s_cmp_ge_i32 s35, s20
	s_cbranch_scc1 .Lmy533_exit
	s_mov_b32 s8, s65
	s_mov_b32 s65, s37
	s_branch .Lmy533
